# v31 + the same sw_layers load de-serialisation in the MLP-down GEMM phase tail copy (layers 1-3)
# baseline (speedup 1.0000x reference)
; __device__ __forceinline__ void sw_layers(const Args& a, int l_lo, int l_hi, int wb, int nwb) {
;     ...
;         for (int u = 0; u < 2; ++u) {
;             float acc[5] = {0.f, 0.f, 0.f, 0.f, 0.f};
; #pragma unroll
;             for (int hseg = 0; hseg < 2; ++hseg) {
;                 const int k0 = hseg * 512 + 8 * lane;
;                 float wf[8]; unpack8(wv[u][hseg], wf);
; #pragma unroll
;                 for (int bb = 0; bb < 5; ++bb) {
;                     const f32x4 s0 = *(const f32x4*)(shp[u] + (size_t)bb * NMODC + k0), s1 = *(const f32x4*)(shp[u] + (size_t)bb * NMODC + k0 + 4);
;                     acc[bb] += s0[0] * wf[0] + s0[1] * wf[1] + s0[2] * wf[2] + s0[3] * wf[3] + s1[0] * wf[4] + s1[1] * wf[5] + s1[2] * wf[6] + s1[3] * wf[7];
;                 }
;             }
.LBB0_284:
	s_or_b64 exec, exec, s[4:5]
	v_readlane_b32 s72, v251, 0
	v_mul_hi_i32_i24_e32 v29, 0x1e000, v30
	v_mul_i32_i24_e32 v28, 0x1e000, v30
	v_readlane_b32 s86, v251, 14
	v_readlane_b32 s87, v251, 15
	v_mov_b32_e32 v23, 0x3000
	v_cndmask_b32_e64 v206, v23, 0, s[0:1]
	v_lshl_add_u64 v[28:29], s[86:87], 0, v[28:29]
	v_lshl_add_u64 v[28:29], v[28:29], 0, v[206:207]
	v_lshlrev_b32_e32 v206, 2, v18
	v_lshl_add_u64 v[176:177], v[28:29], 0, v[206:207]
	s_mov_b64 s[98:99], 0x6000
	v_lshl_add_u64 v[88:89], v[176:177], 0, s[98:99]
	s_mov_b64 s[98:99], 0xc000
	v_lshl_add_u64 v[90:91], v[176:177], 0, s[98:99]
	s_mov_b64 s[98:99], 0x12000
	v_lshl_add_u64 v[92:93], v[176:177], 0, s[98:99]
	s_mov_b64 s[98:99], 0x18000
	v_lshl_add_u64 v[94:95], v[176:177], 0, s[98:99]
	global_load_dwordx4 v[96:99], v[176:177], off
	global_load_dwordx4 v[100:103], v[176:177], off offset:16
	global_load_dwordx4 v[104:107], v[176:177], off offset:2048
	global_load_dwordx4 v[108:111], v[176:177], off offset:2064
	global_load_dwordx4 v[112:115], v[88:89], off
	global_load_dwordx4 v[116:119], v[88:89], off offset:16
	global_load_dwordx4 v[120:123], v[88:89], off offset:2048
	global_load_dwordx4 v[124:127], v[88:89], off offset:2064
	global_load_dwordx4 v[128:131], v[90:91], off
	global_load_dwordx4 v[132:135], v[90:91], off offset:16
	global_load_dwordx4 v[136:139], v[90:91], off offset:2048
	global_load_dwordx4 v[140:143], v[90:91], off offset:2064
	global_load_dwordx4 v[144:147], v[92:93], off
	global_load_dwordx4 v[148:151], v[92:93], off offset:16
	global_load_dwordx4 v[152:155], v[92:93], off offset:2048
	global_load_dwordx4 v[156:159], v[92:93], off offset:2064
	global_load_dwordx4 v[160:163], v[94:95], off
	global_load_dwordx4 v[164:167], v[94:95], off offset:16
	global_load_dwordx4 v[168:171], v[94:95], off offset:2048
	global_load_dwordx4 v[172:175], v[94:95], off offset:2064
	s_waitcnt vmcnt(0)
	v_lshlrev_b32_e32 v23, 16, v14
	v_and_b32_e32 v52, 0xffff0000, v14
	v_lshlrev_b32_e32 v53, 16, v15
	v_and_b32_e32 v54, 0xffff0000, v15
	v_lshl_add_u64 v[14:15], v[28:29], 0, v[206:207]
	s_nop 0
	s_nop 0
	v_lshlrev_b32_e32 v55, 16, v16
	v_and_b32_e32 v56, 0xffff0000, v16
	v_lshlrev_b32_e32 v57, 16, v17
	v_and_b32_e32 v58, 0xffff0000, v17
	s_mov_b64 s[0:1], 0x6000
	v_and_b32_e32 v63, 0xffff0000, v13
	s_mov_b64 s[4:5], -1
	v_readlane_b32 s73, v251, 1
	v_readlane_b32 s74, v251, 2
	v_readlane_b32 s75, v251, 3
	v_readlane_b32 s76, v251, 4
	v_readlane_b32 s77, v251, 5
	v_readlane_b32 s78, v251, 6
	v_readlane_b32 s79, v251, 7
	v_readlane_b32 s80, v251, 8
	v_readlane_b32 s81, v251, 9
	v_readlane_b32 s82, v251, 10
	v_readlane_b32 s83, v251, 11
	v_readlane_b32 s84, v251, 12
	v_readlane_b32 s85, v251, 13
	s_waitcnt vmcnt(0)
	v_mul_f32_e32 v16, v97, v52
	v_fmac_f32_e32 v16, v96, v23
	v_fmac_f32_e32 v16, v98, v53
	v_fmac_f32_e32 v16, v99, v54
	v_fmac_f32_e32 v16, v100, v55
	v_fmac_f32_e32 v16, v101, v56
	v_fmac_f32_e32 v16, v102, v57
	v_fmac_f32_e32 v16, v103, v58
	v_add_f32_e32 v59, 0, v16
	v_lshl_add_u64 v[16:17], v[14:15], 0, s[0:1]
	v_add_co_u32_e64 v30, s[0:1], s7, v14
	s_nop 1
	v_addc_co_u32_e64 v31, s[0:1], 0, v15, s[0:1]
	s_nop 0
	s_nop 0
	s_mov_b64 s[0:1], 0xc000
	v_lshl_add_u64 v[28:29], v[14:15], 0, s[0:1]
	s_mov_b32 s0, 0xc000
	s_waitcnt vmcnt(1)
	v_mul_f32_e32 v16, v113, v52
	v_fmac_f32_e32 v16, v112, v23
	v_fmac_f32_e32 v16, v114, v53
	v_fmac_f32_e32 v16, v115, v54
	s_waitcnt vmcnt(0)
	v_fmac_f32_e32 v16, v116, v55
	v_fmac_f32_e32 v16, v117, v56
	v_fmac_f32_e32 v16, v118, v57
	v_fmac_f32_e32 v16, v119, v58
	v_add_f32_e32 v60, 0, v16
	v_add_co_u32_e64 v16, s[0:1], s0, v14
	s_nop 1
	v_addc_co_u32_e64 v17, s[0:1], 0, v15, s[0:1]
	s_nop 0
	s_nop 0
	s_mov_b64 s[0:1], 0x12000
	v_lshl_add_u64 v[32:33], v[14:15], 0, s[0:1]
	s_mov_b32 s0, 0x12000
	s_waitcnt vmcnt(1)
	v_mul_f32_e32 v28, v129, v52
	v_fmac_f32_e32 v28, v128, v23
	v_fmac_f32_e32 v28, v130, v53
	v_fmac_f32_e32 v28, v131, v54
	s_waitcnt vmcnt(0)
	v_fmac_f32_e32 v28, v132, v55
	v_fmac_f32_e32 v28, v133, v56
	v_fmac_f32_e32 v28, v134, v57
	v_fmac_f32_e32 v28, v135, v58
	v_add_f32_e32 v61, 0, v28
	v_add_co_u32_e64 v28, s[0:1], s0, v14
	s_nop 1
	v_addc_co_u32_e64 v29, s[0:1], 0, v15, s[0:1]
	s_nop 0
	s_nop 0
	s_mov_b64 s[0:1], 0x18000
	s_waitcnt vmcnt(1)
	v_mul_f32_e32 v32, v145, v52
	v_fmac_f32_e32 v32, v144, v23
	v_fmac_f32_e32 v32, v146, v53
	v_fmac_f32_e32 v32, v147, v54
	s_waitcnt vmcnt(0)
	v_fmac_f32_e32 v32, v148, v55
	v_fmac_f32_e32 v32, v149, v56
	v_fmac_f32_e32 v32, v150, v57
	v_fmac_f32_e32 v32, v151, v58
	v_lshl_add_u64 v[48:49], v[14:15], 0, s[0:1]
	s_mov_b32 s0, 0x18000
	v_add_f32_e32 v62, 0, v32
	v_add_co_u32_e64 v32, s[0:1], s0, v14
	s_nop 1
	v_addc_co_u32_e64 v33, s[0:1], 0, v15, s[0:1]
	s_nop 0
	s_nop 0
	s_nop 0
	s_mov_b64 s[0:1], 0x6800
	s_waitcnt vmcnt(1)
	v_mul_f32_e32 v45, v161, v52
	v_fmac_f32_e32 v45, v160, v23
	v_fmac_f32_e32 v45, v162, v53
	v_fmac_f32_e32 v45, v163, v54
	s_waitcnt vmcnt(0)
	v_fmac_f32_e32 v45, v164, v55
	v_fmac_f32_e32 v45, v165, v56
	v_fmac_f32_e32 v45, v166, v57
	v_fmac_f32_e32 v45, v167, v58
	v_add_f32_e32 v23, 0, v45
	v_lshlrev_b32_e32 v52, 16, v10
	v_and_b32_e32 v53, 0xffff0000, v10
	v_lshlrev_b32_e32 v54, 16, v11
	v_and_b32_e32 v55, 0xffff0000, v11
	v_lshlrev_b32_e32 v56, 16, v12
	v_and_b32_e32 v57, 0xffff0000, v12
	v_lshlrev_b32_e32 v58, 16, v13
	s_nop 0
	s_nop 0
	s_waitcnt vmcnt(0)
	v_mul_f32_e32 v45, v105, v53
	v_fmac_f32_e32 v45, v104, v52
	v_fmac_f32_e32 v45, v106, v54
	v_fmac_f32_e32 v45, v107, v55
	v_fmac_f32_e32 v45, v108, v56
	v_fmac_f32_e32 v45, v109, v57
	v_fmac_f32_e32 v45, v110, v58
	v_fmac_f32_e32 v45, v111, v63
	v_add_f32_e32 v10, v59, v45
	v_lshl_add_u64 v[12:13], v[14:15], 0, s[0:1]
	s_nop 0
	s_nop 0
	s_mov_b64 s[0:1], 0xc800
	v_lshl_add_u64 v[30:31], v[14:15], 0, s[0:1]
	s_mov_b64 s[0:1], 0x12800
	s_waitcnt vmcnt(1)
; __device__ __forceinline__ void sw_layers(const Args& a, int l_lo, int l_hi, int wb, int nwb) {
;     ...
;             for (int hseg = 0; hseg < 2; ++hseg) {
;                 const int k0 = hseg * 512 + 8 * lane;
;                 float wf[8]; unpack8(wv[u][hseg], wf);
; #pragma unroll
;                 for (int bb = 0; bb < 5; ++bb) {
;                     const f32x4 s0 = *(const f32x4*)(shp[u] + (size_t)bb * NMODC + k0), s1 = *(const f32x4*)(shp[u] + (size_t)bb * NMODC + k0 + 4);
;                     acc[bb] += s0[0] * wf[0] + s0[1] * wf[1] + s0[2] * wf[2] + s0[3] * wf[3] + s1[0] * wf[4] + s1[1] * wf[5] + s1[2] * wf[6] + s1[3] * wf[7];
;                 }
;             }
; #pragma unroll
;             for (int bb = 0; bb < 5; ++bb) acc[bb] = wave_sum(acc[bb]);
;             if (lane == 0 && okp[u]) {
; #pragma unroll
;                 for (int bb = 0; bb < 5; ++bb) dstp[u][(size_t)bb * ldp[u]] = acc[bb];
;             }
	v_mul_f32_e32 v11, v121, v53
	v_fmac_f32_e32 v11, v120, v52
	v_fmac_f32_e32 v11, v122, v54
	v_fmac_f32_e32 v11, v123, v55
	s_waitcnt vmcnt(0)
	v_fmac_f32_e32 v11, v124, v56
	v_fmac_f32_e32 v11, v125, v57
	v_fmac_f32_e32 v11, v126, v58
	v_fmac_f32_e32 v11, v127, v63
	s_nop 0
	s_nop 0
	v_add_f32_e32 v12, v60, v11
	v_lshl_add_u64 v[16:17], v[14:15], 0, s[0:1]
	s_mov_b64 s[0:1], 0x18800
	s_waitcnt vmcnt(1)
	v_mul_f32_e32 v11, v137, v53
	v_fmac_f32_e32 v11, v136, v52
	v_fmac_f32_e32 v11, v138, v54
	v_fmac_f32_e32 v11, v139, v55
	s_nop 0
	s_nop 0
	s_nop 0
	s_waitcnt vmcnt(2)
	v_fmac_f32_e32 v11, v140, v56
	v_fmac_f32_e32 v11, v141, v57
	v_fmac_f32_e32 v11, v142, v58
	v_fmac_f32_e32 v11, v143, v63
	v_add_f32_e32 v11, v61, v11
	s_waitcnt vmcnt(1)
	v_mul_f32_e32 v13, v153, v53
	v_fmac_f32_e32 v13, v152, v52
	v_fmac_f32_e32 v13, v154, v54
	v_lshl_add_u64 v[28:29], v[14:15], 0, s[0:1]
	v_fmac_f32_e32 v13, v155, v55
	s_nop 0
	s_nop 0
	s_nop 0
	s_waitcnt vmcnt(2)
	v_fmac_f32_e32 v13, v156, v56
	v_fmac_f32_e32 v13, v157, v57
	v_fmac_f32_e32 v13, v158, v58
	v_fmac_f32_e32 v13, v159, v63
	v_add_f32_e32 v13, v62, v13
	s_waitcnt vmcnt(1)
	v_mul_f32_e32 v15, v169, v53
	v_fmac_f32_e32 v15, v168, v52
	v_fmac_f32_e32 v15, v170, v54
	v_fmac_f32_e32 v15, v171, v55
	s_waitcnt vmcnt(0)
	v_fmac_f32_e32 v15, v172, v56
	v_fmac_f32_e32 v15, v173, v57
	v_fmac_f32_e32 v15, v174, v58
	v_fmac_f32_e32 v15, v175, v63
	v_add_f32_e32 v14, v23, v15
	ds_bpermute_b32 v15, v38, v10
	ds_bpermute_b32 v16, v38, v12
	ds_bpermute_b32 v17, v38, v11
	ds_bpermute_b32 v23, v38, v13
	ds_bpermute_b32 v28, v38, v14
	s_waitcnt lgkmcnt(4)
	v_add_f32_e32 v10, v10, v15
	s_waitcnt lgkmcnt(3)
	v_add_f32_e32 v12, v12, v16
	s_waitcnt lgkmcnt(2)
	v_add_f32_e32 v11, v11, v17
	s_waitcnt lgkmcnt(1)
	v_add_f32_e32 v13, v13, v23
	s_waitcnt lgkmcnt(0)
	v_add_f32_e32 v14, v14, v28
	ds_bpermute_b32 v15, v39, v10
	ds_bpermute_b32 v16, v39, v12
	ds_bpermute_b32 v17, v39, v11
	ds_bpermute_b32 v23, v39, v13
	ds_bpermute_b32 v28, v39, v14
	s_waitcnt lgkmcnt(4)
	v_add_f32_e32 v10, v10, v15
	s_waitcnt lgkmcnt(3)
	v_add_f32_e32 v12, v12, v16
	s_waitcnt lgkmcnt(2)
	v_add_f32_e32 v11, v11, v17
	s_waitcnt lgkmcnt(1)
	v_add_f32_e32 v13, v13, v23
	s_waitcnt lgkmcnt(0)
	v_add_f32_e32 v14, v14, v28
	ds_bpermute_b32 v15, v40, v10
	ds_bpermute_b32 v16, v40, v12
	ds_bpermute_b32 v17, v40, v11
	ds_bpermute_b32 v23, v40, v13
	ds_bpermute_b32 v28, v40, v14
	s_waitcnt lgkmcnt(4)
	v_add_f32_e32 v10, v10, v15
	s_waitcnt lgkmcnt(3)
	v_add_f32_e32 v12, v12, v16
	s_waitcnt lgkmcnt(2)
	v_add_f32_e32 v11, v11, v17
	s_waitcnt lgkmcnt(1)
	v_add_f32_e32 v13, v13, v23
	s_waitcnt lgkmcnt(0)
	v_add_f32_e32 v14, v14, v28
	ds_bpermute_b32 v15, v41, v10
	ds_bpermute_b32 v16, v41, v12
	ds_bpermute_b32 v17, v41, v11
	ds_bpermute_b32 v23, v41, v13
	ds_bpermute_b32 v28, v41, v14
	s_waitcnt lgkmcnt(4)
	v_add_f32_e32 v10, v10, v15
	s_waitcnt lgkmcnt(3)
	v_add_f32_e32 v12, v12, v16
	s_waitcnt lgkmcnt(2)
	v_add_f32_e32 v11, v11, v17
	s_waitcnt lgkmcnt(1)
	v_add_f32_e32 v13, v13, v23
	s_waitcnt lgkmcnt(0)
	v_add_f32_e32 v14, v14, v28
	ds_bpermute_b32 v15, v42, v10
	ds_bpermute_b32 v16, v42, v12
	ds_bpermute_b32 v17, v42, v11
	ds_bpermute_b32 v23, v42, v13
	ds_bpermute_b32 v28, v42, v14
	s_waitcnt lgkmcnt(4)
	v_add_f32_e32 v10, v10, v15
	s_waitcnt lgkmcnt(3)
	v_add_f32_e32 v12, v12, v16
	s_waitcnt lgkmcnt(2)
	v_add_f32_e32 v11, v11, v17
	s_waitcnt lgkmcnt(1)
	v_add_f32_e32 v13, v13, v23
	s_waitcnt lgkmcnt(0)
	v_add_f32_e32 v14, v14, v28
	ds_bpermute_b32 v15, v43, v10
	ds_bpermute_b32 v16, v43, v12
	ds_bpermute_b32 v17, v43, v11
	ds_bpermute_b32 v23, v43, v13
	ds_bpermute_b32 v28, v43, v14
	s_and_saveexec_b64 s[0:1], vcc
	s_cbranch_execz .LBB0_286
	s_waitcnt lgkmcnt(4)
	v_add_f32_e32 v10, v10, v15
	s_waitcnt lgkmcnt(2)
	v_add_f32_e32 v17, v11, v17
	global_store_dword v[24:25], v10, off
	v_lshlrev_b32_e32 v10, 2, v26
	v_mov_b32_e32 v11, v207
	s_waitcnt lgkmcnt(1)
	v_add_f32_e32 v23, v13, v23
	v_add_f32_e32 v16, v12, v16
	v_lshl_add_u64 v[12:13], v[24:25], 0, v[10:11]
	global_store_dword v[12:13], v16, off
	v_lshl_add_u64 v[12:13], v[12:13], 0, v[10:11]
	global_store_dword v[12:13], v17, off
	v_lshl_add_u64 v[12:13], v[12:13], 0, v[10:11]
	s_waitcnt lgkmcnt(0)
	v_add_f32_e32 v14, v14, v28
	v_lshl_add_u64 v[10:11], v[12:13], 0, v[10:11]
	s_orn2_b64 s[4:5], s[40:41], exec
	global_store_dword v[12:13], v23, off
	global_store_dword v[10:11], v14, off
; __device__ __forceinline__ void sw_layers(const Args& a, int l_lo, int l_hi, int wb, int nwb) {
;     ...
;             shp[u] = mod + (size_t)l * 5 * NMODC + (first ? 0 : 3) * DM;
;             dstp[u] = first ? (float*)(a.ws + WS_SWIN) + (size_t)l * 5 * DIN + n : (float*)(a.ws + WS_SW1) + (size_t)l * 5 * DFF + n; ldp[u] = first ? DIN : DFF;
;         }
; #pragma unroll
;         for (int u = 0; u < 2; ++u) {
;             float acc[5] = {0.f, 0.f, 0.f, 0.f, 0.f};
; #pragma unroll
;             for (int hseg = 0; hseg < 2; ++hseg) {
;                 const int k0 = hseg * 512 + 8 * lane;
;                 float wf[8]; unpack8(wv[u][hseg], wf);
; #pragma unroll
;                 for (int bb = 0; bb < 5; ++bb) {
;                     const f32x4 s0 = *(const f32x4*)(shp[u] + (size_t)bb * NMODC + k0), s1 = *(const f32x4*)(shp[u] + (size_t)bb * NMODC + k0 + 4);
;                     acc[bb] += s0[0] * wf[0] + s0[1] * wf[1] + s0[2] * wf[2] + s0[3] * wf[3] + s1[0] * wf[4] + s1[1] * wf[5] + s1[2] * wf[6] + s1[3] * wf[7];
.LBB0_286:
	s_or_b64 exec, exec, s[0:1]
	v_readlane_b32 s72, v251, 0
	v_mul_hi_i32_i24_e32 v11, 0x1e000, v27
	v_mul_i32_i24_e32 v10, 0x1e000, v27
	v_readlane_b32 s86, v251, 14
	v_readlane_b32 s87, v251, 15
	v_mov_b32_e32 v12, 0x3000
	v_cndmask_b32_e64 v12, v12, 0, s[38:39]
	v_lshl_add_u64 v[10:11], s[86:87], 0, v[10:11]
	v_mov_b32_e32 v13, v207
	v_lshl_add_u64 v[10:11], v[10:11], 0, v[12:13]
	s_waitcnt lgkmcnt(1)
	v_lshlrev_b32_e32 v23, 16, v6
	v_and_b32_e32 v32, 0xffff0000, v6
	v_lshlrev_b32_e32 v33, 16, v7
	v_and_b32_e32 v44, 0xffff0000, v7
	v_lshl_add_u64 v[6:7], v[10:11], 0, v[206:207]
	s_mov_b64 s[98:99], 0x6000
	v_lshl_add_u64 v[88:89], v[6:7], 0, s[98:99]
	s_mov_b64 s[98:99], 0xc000
	v_lshl_add_u64 v[90:91], v[6:7], 0, s[98:99]
	s_mov_b64 s[98:99], 0x12000
	v_lshl_add_u64 v[92:93], v[6:7], 0, s[98:99]
	s_mov_b64 s[98:99], 0x18000
	v_lshl_add_u64 v[94:95], v[6:7], 0, s[98:99]
	global_load_dwordx4 v[96:99], v[6:7], off
	global_load_dwordx4 v[100:103], v[6:7], off offset:16
	global_load_dwordx4 v[104:107], v[6:7], off offset:2048
	global_load_dwordx4 v[108:111], v[6:7], off offset:2064
	global_load_dwordx4 v[112:115], v[88:89], off
	global_load_dwordx4 v[116:119], v[88:89], off offset:16
	global_load_dwordx4 v[120:123], v[88:89], off offset:2048
	global_load_dwordx4 v[124:127], v[88:89], off offset:2064
	global_load_dwordx4 v[128:131], v[90:91], off
	global_load_dwordx4 v[132:135], v[90:91], off offset:16
	global_load_dwordx4 v[136:139], v[90:91], off offset:2048
	global_load_dwordx4 v[140:143], v[90:91], off offset:2064
	global_load_dwordx4 v[144:147], v[92:93], off
	global_load_dwordx4 v[148:151], v[92:93], off offset:16
	global_load_dwordx4 v[152:155], v[92:93], off offset:2048
	global_load_dwordx4 v[156:159], v[92:93], off offset:2064
	global_load_dwordx4 v[160:163], v[94:95], off
	global_load_dwordx4 v[164:167], v[94:95], off offset:16
	global_load_dwordx4 v[168:171], v[94:95], off offset:2048
	global_load_dwordx4 v[172:175], v[94:95], off offset:2064
	s_waitcnt vmcnt(0)
	v_lshlrev_b32_e32 v45, 16, v8
	v_and_b32_e32 v46, 0xffff0000, v8
	v_lshlrev_b32_e32 v47, 16, v9
	v_and_b32_e32 v48, 0xffff0000, v9
	s_nop 0
	s_nop 0
	s_mov_b64 s[0:1], 0x6000
	s_xor_b64 s[4:5], s[4:5], -1
	v_readlane_b32 s73, v251, 1
	v_readlane_b32 s74, v251, 2
	v_readlane_b32 s75, v251, 3
	v_readlane_b32 s76, v251, 4
	v_readlane_b32 s77, v251, 5
	v_readlane_b32 s78, v251, 6
	v_readlane_b32 s79, v251, 7
	v_readlane_b32 s80, v251, 8
	v_readlane_b32 s81, v251, 9
	v_readlane_b32 s82, v251, 10
	v_readlane_b32 s83, v251, 11
	v_readlane_b32 s84, v251, 12
	v_readlane_b32 s85, v251, 13
	s_waitcnt vmcnt(0)
	v_mul_f32_e32 v13, v97, v32
	v_fmac_f32_e32 v13, v96, v23
	v_fmac_f32_e32 v13, v98, v33
	v_fmac_f32_e32 v13, v99, v44
	v_fmac_f32_e32 v13, v100, v45
	v_fmac_f32_e32 v13, v101, v46
	v_fmac_f32_e32 v13, v102, v47
	v_fmac_f32_e32 v13, v103, v48
	v_lshl_add_u64 v[14:15], v[6:7], 0, s[0:1]
	v_add_co_u32_e64 v12, s[0:1], s7, v6
	v_add_f32_e32 v49, 0, v13
	s_nop 0
	v_addc_co_u32_e64 v13, s[0:1], 0, v7, s[0:1]
	s_nop 0
	s_nop 0
	s_nop 0
	s_mov_b64 s[0:1], 0xc000
	s_waitcnt vmcnt(1)
	v_mul_f32_e32 v9, v113, v32
	v_fmac_f32_e32 v9, v112, v23
	v_fmac_f32_e32 v9, v114, v33
	v_fmac_f32_e32 v9, v115, v44
	s_waitcnt vmcnt(0)
	v_fmac_f32_e32 v9, v116, v45
	v_fmac_f32_e32 v9, v117, v46
	v_fmac_f32_e32 v9, v118, v47
	v_lshl_add_u64 v[10:11], v[6:7], 0, s[0:1]
	s_mov_b32 s0, 0xc000
	v_fmac_f32_e32 v9, v119, v48
	v_add_co_u32_e64 v8, s[0:1], s0, v6
	v_add_f32_e32 v50, 0, v9
	s_nop 0
	v_addc_co_u32_e64 v9, s[0:1], 0, v7, s[0:1]
	s_nop 0
	s_nop 0
	s_mov_b64 s[0:1], 0x12000
	s_waitcnt vmcnt(1)
	v_mul_f32_e32 v10, v129, v32
	v_fmac_f32_e32 v10, v128, v23
	v_fmac_f32_e32 v10, v130, v33
	v_fmac_f32_e32 v10, v131, v44
	s_waitcnt vmcnt(0)
	v_fmac_f32_e32 v10, v132, v45
	v_fmac_f32_e32 v10, v133, v46
	v_fmac_f32_e32 v10, v134, v47
	v_fmac_f32_e32 v10, v135, v48
	v_lshl_add_u64 v[24:25], v[6:7], 0, s[0:1]
	s_mov_b32 s0, 0x12000
	v_add_f32_e32 v51, 0, v10
	v_add_co_u32_e64 v10, s[0:1], s0, v6
	s_nop 1
	v_addc_co_u32_e64 v11, s[0:1], 0, v7, s[0:1]
	s_nop 0
	s_nop 0
	s_nop 0
	s_mov_b64 s[0:1], 0x18000
	s_waitcnt vmcnt(1)
	v_mul_f32_e32 v15, v145, v32
	v_fmac_f32_e32 v15, v144, v23
	v_fmac_f32_e32 v15, v146, v33
	v_fmac_f32_e32 v15, v147, v44
	s_waitcnt vmcnt(0)
	v_fmac_f32_e32 v15, v148, v45
	v_fmac_f32_e32 v15, v149, v46
	v_fmac_f32_e32 v15, v150, v47
	v_lshl_add_u64 v[16:17], v[6:7], 0, s[0:1]
	s_mov_b32 s0, 0x18000
	v_fmac_f32_e32 v15, v151, v48
	v_add_co_u32_e64 v14, s[0:1], s0, v6
	v_add_f32_e32 v52, 0, v15
	s_nop 0
	v_addc_co_u32_e64 v15, s[0:1], 0, v7, s[0:1]
	s_nop 0
	s_waitcnt lgkmcnt(0)
	s_nop 0
	v_lshlrev_b32_e32 v17, 16, v2
	s_mov_b64 s[0:1], 0x6800
	s_waitcnt vmcnt(1)
	v_mul_f32_e32 v16, v161, v32
	v_fmac_f32_e32 v16, v160, v23
	v_fmac_f32_e32 v16, v162, v33
	v_fmac_f32_e32 v16, v163, v44
	s_waitcnt vmcnt(0)
; __device__ __forceinline__ void sw_layers(const Args& a, int l_lo, int l_hi, int wb, int nwb) {
;     ...
;             for (int hseg = 0; hseg < 2; ++hseg) {
;                 const int k0 = hseg * 512 + 8 * lane;
;                 float wf[8]; unpack8(wv[u][hseg], wf);
; #pragma unroll
;                 for (int bb = 0; bb < 5; ++bb) {
;                     const f32x4 s0 = *(const f32x4*)(shp[u] + (size_t)bb * NMODC + k0), s1 = *(const f32x4*)(shp[u] + (size_t)bb * NMODC + k0 + 4);
;                     acc[bb] += s0[0] * wf[0] + s0[1] * wf[1] + s0[2] * wf[2] + s0[3] * wf[3] + s1[0] * wf[4] + s1[1] * wf[5] + s1[2] * wf[6] + s1[3] * wf[7];
;                 }
;             }
; #pragma unroll
;             for (int bb = 0; bb < 5; ++bb) acc[bb] = wave_sum(acc[bb]);
;             if (lane == 0 && okp[u]) {
; #pragma unroll
;                 for (int bb = 0; bb < 5; ++bb) dstp[u][(size_t)bb * ldp[u]] = acc[bb];
;             }
	v_fmac_f32_e32 v16, v164, v45
	v_fmac_f32_e32 v16, v165, v46
	v_fmac_f32_e32 v16, v166, v47
	v_and_b32_e32 v23, 0xffff0000, v2
	v_lshlrev_b32_e32 v32, 16, v3
	v_and_b32_e32 v33, 0xffff0000, v3
	v_lshlrev_b32_e32 v44, 16, v4
	v_and_b32_e32 v45, 0xffff0000, v4
	v_lshlrev_b32_e32 v46, 16, v5
	v_and_b32_e32 v47, 0xffff0000, v5
	s_nop 0
	s_nop 0
	v_fmac_f32_e32 v16, v167, v48
	v_add_f32_e32 v16, 0, v16
	s_waitcnt vmcnt(0)
	v_mul_f32_e32 v25, v105, v23
	v_fmac_f32_e32 v25, v104, v17
	v_fmac_f32_e32 v25, v106, v32
	v_fmac_f32_e32 v25, v107, v33
	v_fmac_f32_e32 v25, v108, v44
	v_fmac_f32_e32 v25, v109, v45
	v_fmac_f32_e32 v25, v110, v46
	v_fmac_f32_e32 v25, v111, v47
	v_add_f32_e32 v2, v49, v25
	v_lshl_add_u64 v[4:5], v[6:7], 0, s[0:1]
	s_nop 0
	s_nop 0
	s_mov_b64 s[0:1], 0xc800
	v_lshl_add_u64 v[12:13], v[6:7], 0, s[0:1]
	s_mov_b64 s[0:1], 0x12800
	s_waitcnt vmcnt(1)
	v_mul_f32_e32 v3, v121, v23
	v_fmac_f32_e32 v3, v120, v17
	v_fmac_f32_e32 v3, v122, v32
	v_fmac_f32_e32 v3, v123, v33
	s_waitcnt vmcnt(0)
	v_fmac_f32_e32 v3, v124, v44
	v_fmac_f32_e32 v3, v125, v45
	v_fmac_f32_e32 v3, v126, v46
	v_fmac_f32_e32 v3, v127, v47
	s_nop 0
	s_nop 0
	v_add_f32_e32 v4, v50, v3
	v_lshl_add_u64 v[12:13], v[6:7], 0, s[0:1]
	s_mov_b64 s[0:1], 0x18800
	s_waitcnt vmcnt(1)
	v_mul_f32_e32 v3, v137, v23
	v_fmac_f32_e32 v3, v136, v17
	v_fmac_f32_e32 v3, v138, v32
	v_fmac_f32_e32 v3, v139, v33
	s_nop 0
	s_nop 0
	s_nop 0
	s_waitcnt vmcnt(2)
	v_fmac_f32_e32 v3, v140, v44
	v_fmac_f32_e32 v3, v141, v45
	v_fmac_f32_e32 v3, v142, v46
	v_fmac_f32_e32 v3, v143, v47
	v_add_f32_e32 v3, v51, v3
	s_waitcnt vmcnt(1)
	v_mul_f32_e32 v5, v153, v23
	v_fmac_f32_e32 v5, v152, v17
	v_fmac_f32_e32 v5, v154, v32
	v_fmac_f32_e32 v5, v155, v33
	v_lshl_add_u64 v[10:11], v[6:7], 0, s[0:1]
	s_nop 0
	s_nop 0
	s_nop 0
	s_waitcnt vmcnt(2)
	v_fmac_f32_e32 v5, v156, v44
	v_fmac_f32_e32 v5, v157, v45
	v_fmac_f32_e32 v5, v158, v46
	v_fmac_f32_e32 v5, v159, v47
	v_add_f32_e32 v5, v52, v5
	s_waitcnt vmcnt(1)
	v_mul_f32_e32 v7, v169, v23
	v_fmac_f32_e32 v7, v168, v17
	v_fmac_f32_e32 v7, v170, v32
	v_fmac_f32_e32 v7, v171, v33
	s_waitcnt vmcnt(0)
	v_fmac_f32_e32 v7, v172, v44
	v_fmac_f32_e32 v7, v173, v45
	v_fmac_f32_e32 v7, v174, v46
	v_fmac_f32_e32 v7, v175, v47
	v_add_f32_e32 v6, v16, v7
	ds_bpermute_b32 v7, v38, v2
	ds_bpermute_b32 v8, v38, v4
	ds_bpermute_b32 v9, v38, v3
	ds_bpermute_b32 v10, v38, v5
	ds_bpermute_b32 v11, v38, v6
	s_waitcnt lgkmcnt(4)
	v_add_f32_e32 v2, v2, v7
	s_waitcnt lgkmcnt(3)
	v_add_f32_e32 v4, v4, v8
	s_waitcnt lgkmcnt(2)
	v_add_f32_e32 v3, v3, v9
	s_waitcnt lgkmcnt(1)
	v_add_f32_e32 v5, v5, v10
	s_waitcnt lgkmcnt(0)
	v_add_f32_e32 v6, v6, v11
	ds_bpermute_b32 v7, v39, v2
	ds_bpermute_b32 v8, v39, v4
	ds_bpermute_b32 v9, v39, v3
	ds_bpermute_b32 v10, v39, v5
	ds_bpermute_b32 v11, v39, v6
	s_waitcnt lgkmcnt(4)
	v_add_f32_e32 v2, v2, v7
	s_waitcnt lgkmcnt(3)
	v_add_f32_e32 v4, v4, v8
	s_waitcnt lgkmcnt(2)
	v_add_f32_e32 v3, v3, v9
	s_waitcnt lgkmcnt(1)
	v_add_f32_e32 v5, v5, v10
	s_waitcnt lgkmcnt(0)
	v_add_f32_e32 v6, v6, v11
	ds_bpermute_b32 v7, v40, v2
	ds_bpermute_b32 v8, v40, v4
	ds_bpermute_b32 v9, v40, v3
	ds_bpermute_b32 v10, v40, v5
	ds_bpermute_b32 v11, v40, v6
	s_waitcnt lgkmcnt(4)
	v_add_f32_e32 v2, v2, v7
	s_waitcnt lgkmcnt(3)
	v_add_f32_e32 v4, v4, v8
	s_waitcnt lgkmcnt(2)
	v_add_f32_e32 v3, v3, v9
	s_waitcnt lgkmcnt(1)
	v_add_f32_e32 v5, v5, v10
	s_waitcnt lgkmcnt(0)
	v_add_f32_e32 v6, v6, v11
	ds_bpermute_b32 v7, v41, v2
	ds_bpermute_b32 v8, v41, v4
	ds_bpermute_b32 v9, v41, v3
	ds_bpermute_b32 v10, v41, v5
	ds_bpermute_b32 v11, v41, v6
	s_waitcnt lgkmcnt(4)
	v_add_f32_e32 v2, v2, v7
	s_waitcnt lgkmcnt(3)
	v_add_f32_e32 v4, v4, v8
	s_waitcnt lgkmcnt(2)
	v_add_f32_e32 v3, v3, v9
	s_waitcnt lgkmcnt(1)
	v_add_f32_e32 v5, v5, v10
	s_waitcnt lgkmcnt(0)
	v_add_f32_e32 v6, v6, v11
	ds_bpermute_b32 v7, v42, v2
	ds_bpermute_b32 v8, v42, v4
	ds_bpermute_b32 v9, v42, v3
	ds_bpermute_b32 v10, v42, v5
	ds_bpermute_b32 v11, v42, v6
	s_waitcnt lgkmcnt(4)
	v_add_f32_e32 v2, v2, v7
	s_waitcnt lgkmcnt(3)
	v_add_f32_e32 v4, v4, v8
	s_waitcnt lgkmcnt(2)
	v_add_f32_e32 v3, v3, v9
	s_waitcnt lgkmcnt(1)
	v_add_f32_e32 v5, v5, v10
	s_waitcnt lgkmcnt(0)
	v_add_f32_e32 v6, v6, v11
	ds_bpermute_b32 v7, v43, v2
	ds_bpermute_b32 v8, v43, v4
	ds_bpermute_b32 v9, v43, v3
	ds_bpermute_b32 v10, v43, v5
	ds_bpermute_b32 v11, v43, v6
	s_and_saveexec_b64 s[0:1], s[4:5]
	s_cbranch_execz .LBB0_275
	s_waitcnt lgkmcnt(4)
	v_add_f32_e32 v2, v2, v7
	v_lshlrev_b32_e32 v206, 2, v22
	s_waitcnt lgkmcnt(2)
	v_add_f32_e32 v9, v3, v9
	v_add_f32_e32 v4, v4, v8
	global_store_dword v[20:21], v2, off
	v_lshl_add_u64 v[2:3], v[20:21], 0, v[206:207]
	global_store_dword v[2:3], v4, off
	v_lshl_add_u64 v[2:3], v[2:3], 0, v[206:207]
	s_waitcnt lgkmcnt(1)
	v_add_f32_e32 v5, v5, v10
	global_store_dword v[2:3], v9, off
	v_lshl_add_u64 v[2:3], v[2:3], 0, v[206:207]
	s_waitcnt lgkmcnt(0)
	v_add_f32_e32 v6, v6, v11
	global_store_dword v[2:3], v5, off
	v_lshl_add_u64 v[2:3], v[2:3], 0, v[206:207]
	global_store_dword v[2:3], v6, off
	s_branch .LBB0_275
